# proj tail (cols 2048-2095): all 256 workgroups, 32x48 block each, K split over 8 waves with LDS f32 reduction; attention packed f32 ops split to scalar
# speedup vs baseline: 1.0597x; 1.0233x over previous
.LBB0_197:
	s_cmpk_gt_i32 s2, 0xff
	s_cbranch_scc1 .LBB0_426
	s_waitcnt vmcnt(0)
	v_lshrrev_b32_e32 v0, 6, v204
	v_and_b32_e32 v1, 63, v204
	v_and_b32_e32 v2, 15, v1
	v_lshrrev_b32_e32 v3, 4, v1
	v_lshlrev_b32_e32 v4, 8, v0
	v_lshl_add_u32 v4, v3, 4, v4
	s_lshl_b32 s4, s2, 16
	v_lshl_add_u32 v5, v2, 11, v4
	v_add_u32_e32 v7, 0x400000, v5
	v_add_u32_e32 v5, s4, v5
	v_add_u32_e32 v6, 0x8000, v5
	v_add_u32_e32 v8, 0x8000, v7
	v_add_u32_e32 v9, 0x10000, v7
	s_add_u32 s6, s34, 0x8a44000
	s_addc_u32 s7, s35, 0
	global_load_dwordx4 v[16:19], v5, s[6:7]
	global_load_dwordx4 v[20:23], v5, s[6:7] offset:64
	global_load_dwordx4 v[24:27], v5, s[6:7] offset:128
	global_load_dwordx4 v[28:31], v5, s[6:7] offset:192
	global_load_dwordx4 v[32:35], v6, s[6:7]
	global_load_dwordx4 v[36:39], v6, s[6:7] offset:64
	global_load_dwordx4 v[40:43], v6, s[6:7] offset:128
	global_load_dwordx4 v[44:47], v6, s[6:7] offset:192
	global_load_dwordx4 v[48:51], v7, s[34:35]
	global_load_dwordx4 v[52:55], v7, s[34:35] offset:64
	global_load_dwordx4 v[56:59], v7, s[34:35] offset:128
	global_load_dwordx4 v[60:63], v7, s[34:35] offset:192
	global_load_dwordx4 v[64:67], v8, s[34:35]
	global_load_dwordx4 v[68:71], v8, s[34:35] offset:64
	global_load_dwordx4 v[72:75], v8, s[34:35] offset:128
	global_load_dwordx4 v[76:79], v8, s[34:35] offset:192
	global_load_dwordx4 v[80:83], v9, s[34:35]
	global_load_dwordx4 v[84:87], v9, s[34:35] offset:64
	global_load_dwordx4 v[88:91], v9, s[34:35] offset:128
	global_load_dwordx4 v[92:95], v9, s[34:35] offset:192
	v_mul_u32_u24_e32 v10, 0x1800, v0
	v_lshl_add_u32 v10, v1, 4, v10
	v_lshlrev_b32_e32 v11, 10, v0
	v_lshl_add_u32 v11, v1, 4, v11
	v_readfirstlane_b32 s5, v0
	s_waitcnt vmcnt(0)
	v_mfma_f32_16x16x32_bf16 v[96:99], v[16:19], v[48:51], 0
	v_mfma_f32_16x16x32_bf16 v[100:103], v[16:19], v[64:67], 0
	v_mfma_f32_16x16x32_bf16 v[104:107], v[16:19], v[80:83], 0
	v_mfma_f32_16x16x32_bf16 v[108:111], v[32:35], v[48:51], 0
	v_mfma_f32_16x16x32_bf16 v[112:115], v[32:35], v[64:67], 0
	v_mfma_f32_16x16x32_bf16 v[116:119], v[32:35], v[80:83], 0
	v_mfma_f32_16x16x32_bf16 v[96:99], v[20:23], v[52:55], v[96:99]
	v_mfma_f32_16x16x32_bf16 v[100:103], v[20:23], v[68:71], v[100:103]
	v_mfma_f32_16x16x32_bf16 v[104:107], v[20:23], v[84:87], v[104:107]
	v_mfma_f32_16x16x32_bf16 v[108:111], v[36:39], v[52:55], v[108:111]
	v_mfma_f32_16x16x32_bf16 v[112:115], v[36:39], v[68:71], v[112:115]
	v_mfma_f32_16x16x32_bf16 v[116:119], v[36:39], v[84:87], v[116:119]
	v_mfma_f32_16x16x32_bf16 v[96:99], v[24:27], v[56:59], v[96:99]
	v_mfma_f32_16x16x32_bf16 v[100:103], v[24:27], v[72:75], v[100:103]
	v_mfma_f32_16x16x32_bf16 v[104:107], v[24:27], v[88:91], v[104:107]
	v_mfma_f32_16x16x32_bf16 v[108:111], v[40:43], v[56:59], v[108:111]
	v_mfma_f32_16x16x32_bf16 v[112:115], v[40:43], v[72:75], v[112:115]
	v_mfma_f32_16x16x32_bf16 v[116:119], v[40:43], v[88:91], v[116:119]
	v_mfma_f32_16x16x32_bf16 v[96:99], v[28:31], v[60:63], v[96:99]
	v_mfma_f32_16x16x32_bf16 v[100:103], v[28:31], v[76:79], v[100:103]
	v_mfma_f32_16x16x32_bf16 v[104:107], v[28:31], v[92:95], v[104:107]
	v_mfma_f32_16x16x32_bf16 v[108:111], v[44:47], v[60:63], v[108:111]
	v_mfma_f32_16x16x32_bf16 v[112:115], v[44:47], v[76:79], v[112:115]
	v_mfma_f32_16x16x32_bf16 v[116:119], v[44:47], v[92:95], v[116:119]
	s_nop 7
	s_nop 3
	ds_write_b128 v10, v[96:99]
	ds_write_b128 v10, v[100:103] offset:1024
	ds_write_b128 v10, v[104:107] offset:2048
	ds_write_b128 v10, v[108:111] offset:3072
	ds_write_b128 v10, v[112:115] offset:4096
	ds_write_b128 v10, v[116:119] offset:5120
	s_waitcnt lgkmcnt(0)
	s_barrier
	s_cmp_gt_u32 s5, 5
	s_cbranch_scc1 .Lpt_done
	ds_read_b128 v[120:123], v11
	ds_read_b128 v[124:127], v11 offset:6144
	ds_read_b128 v[128:131], v11 offset:12288
	ds_read_b128 v[132:135], v11 offset:18432
	ds_read_b128 v[136:139], v11 offset:24576
	ds_read_b128 v[140:143], v11 offset:30720
	ds_read_b128 v[144:147], v11 offset:36864
	ds_read_b128 v[148:151], v11 offset:43008
	s_cmp_gt_u32 s5, 2
	s_cselect_b32 s8, 1, 0
	s_mul_i32 s9, s8, 3
	s_sub_u32 s9, s5, s9
	s_lshl_b32 s10, s2, 5
	s_lshl_b32 s11, s8, 4
	s_add_u32 s10, s10, s11
	v_lshl_add_u32 v12, v3, 2, s10
	s_waitcnt lgkmcnt(6)
	v_add_f32_e32 v120, v120, v124
	v_add_f32_e32 v121, v121, v125
	v_add_f32_e32 v122, v122, v126
	v_add_f32_e32 v123, v123, v127
	s_waitcnt lgkmcnt(5)
	v_add_f32_e32 v120, v120, v128
	v_add_f32_e32 v121, v121, v129
	v_add_f32_e32 v122, v122, v130
	v_add_f32_e32 v123, v123, v131
	s_waitcnt lgkmcnt(4)
	v_add_f32_e32 v120, v120, v132
	v_add_f32_e32 v121, v121, v133
	v_add_f32_e32 v122, v122, v134
	v_add_f32_e32 v123, v123, v135
	s_waitcnt lgkmcnt(3)
	v_add_f32_e32 v120, v120, v136
	v_add_f32_e32 v121, v121, v137
	v_add_f32_e32 v122, v122, v138
	v_add_f32_e32 v123, v123, v139
	s_waitcnt lgkmcnt(2)
	v_add_f32_e32 v120, v120, v140
	v_add_f32_e32 v121, v121, v141
	v_add_f32_e32 v122, v122, v142
	v_add_f32_e32 v123, v123, v143
	s_waitcnt lgkmcnt(1)
	v_add_f32_e32 v120, v120, v144
	v_add_f32_e32 v121, v121, v145
	v_add_f32_e32 v122, v122, v146
	v_add_f32_e32 v123, v123, v147
	s_waitcnt lgkmcnt(0)
	v_add_f32_e32 v120, v120, v148
	v_add_f32_e32 v121, v121, v149
	v_add_f32_e32 v122, v122, v150
	v_add_f32_e32 v123, v123, v151
	s_cmp_eq_u32 s9, 2
	s_cbranch_scc1 .Lpt_dt
	s_lshl_b32 s11, s9, 5
	s_add_u32 s11, s11, 0x28c5000
	s_add_u32 s12, s34, s11
	s_addc_u32 s13, s35, 0
	v_mul_u32_u24_e32 v13, 0x1040, v12
	v_lshl_add_u32 v13, v2, 1, v13
	v_cvt_pk_bf16_f32 v14, v120, v120
	global_store_short v13, v14, s[12:13]
	v_add_u32_e32 v13, 0x1040, v13
	v_cvt_pk_bf16_f32 v14, v121, v121
	global_store_short v13, v14, s[12:13]
	v_add_u32_e32 v13, 0x1040, v13
	v_cvt_pk_bf16_f32 v14, v122, v122
	global_store_short v13, v14, s[12:13]
	v_add_u32_e32 v13, 0x1040, v13
	v_cvt_pk_bf16_f32 v14, v123, v123
	global_store_short v13, v14, s[12:13]
	s_branch .Lpt_done
.Lpt_dt:
	s_add_u32 s12, s34, 0x4944000
	s_addc_u32 s13, s35, 0
	v_lshlrev_b32_e32 v13, 6, v12
	v_lshl_add_u32 v13, v2, 2, v13
	global_store_dword v13, v120, s[12:13]
	global_store_dword v13, v121, s[12:13] offset:64
	global_store_dword v13, v122, s[12:13] offset:128
	global_store_dword v13, v123, s[12:13] offset:192
.Lpt_done:
.LBB0_426:
	s_cmp_gt_i32 s89, 3
	s_cselect_b64 s[4:5], -1, 0
	s_and_b64 s[6:7], s[18:19], s[4:5]
	s_andn2_b64 vcc, exec, s[6:7]
	s_cbranch_vccnz .LBB0_480
	s_waitcnt vmcnt(0)
	s_waitcnt lgkmcnt(0)
	s_barrier
	s_and_saveexec_b64 s[6:7], s[92:93]
	s_cbranch_execz .LBB0_479
	s_waitcnt vmcnt(7)
	v_mov_b32_e32 v0, 0x24000
	s_waitcnt vmcnt(0) expcnt(0) lgkmcnt(0)
	ds_read_b32 v2, v0
	v_mov_b32_e32 v0, 0x24004
	ds_read_b32 v0, v0
	s_waitcnt lgkmcnt(1)
	v_cmp_ne_u32_e32 vcc, 0, v2
	s_cbranch_vccnz .LBB0_443
	s_load_dwordx2 s[12:13], s[0:1], 0x120
	s_load_dword s11, s[0:1], 0x128
	s_add_u32 s8, s34, 0xed0d200
	s_addc_u32 s9, s35, 0
	s_add_u32 s10, s34, 0xed0d400
	s_waitcnt lgkmcnt(0)
	s_mul_i32 s14, s13, s12
	s_mul_i32 s14, s14, s11
	s_addc_u32 s11, s35, 0
	s_add_u32 s12, s34, 0xed0d500
	s_addc_u32 s13, s35, 0
	s_add_u32 s16, s34, 0xed0d600
	s_addc_u32 s17, s35, 0
	s_add_u32 s18, s34, 0xed0d700
	s_addc_u32 s19, s35, 0
	s_add_u32 s20, s34, 0xed0d800
	s_addc_u32 s21, s35, 0
	s_add_u32 s22, s34, 0xed0d900
	s_addc_u32 s23, s35, 0
	s_add_u32 s24, s34, 0xed0da00
	s_addc_u32 s25, s35, 0
	s_add_u32 s26, s34, 0xed0db00
	s_addc_u32 s27, s35, 0
	s_add_u32 s28, s34, 0xed0dc00
	s_addc_u32 s29, s35, 0
	s_add_u32 s30, s34, 0xed0dd00
	s_addc_u32 s31, s35, 0
	s_add_u32 s42, s34, 0xed0de00
	s_addc_u32 s43, s35, 0
	s_add_u32 s44, s34, 0xed0df00
	s_addc_u32 s45, s35, 0
	s_add_u32 s48, s34, 0xed0e000
	s_addc_u32 s49, s35, 0
	s_add_u32 s50, s34, 0xed0e100
	s_addc_u32 s51, s35, 0
	s_add_u32 s56, s34, 0xed0e200
	s_addc_u32 s57, s35, 0
	s_add_u32 s66, s34, 0xed0e300
	s_addc_u32 s67, s35, 0
	s_mov_b32 s15, 1
	v_mov_b32_e32 v16, 0
	s_branch .LBB0_431

.LBB0_929:
	s_add_i32 s4, s7, 1
	s_min_i32 s20, s4, s6
	v_lshlrev_b64 v[66:67], v108, s[20:21]
	v_lshlrev_b64 v[148:149], v110, s[20:21]
	v_mul_hi_u32_u24_e32 v161, s20, v100
	v_mul_u32_u24_e32 v160, s20, v100
	s_lshl_b32 s20, s20, 8
	s_bitcmp1_b32 s7, 0
	s_cselect_b32 s5, 0xac00, 0
	v_or_b32_e32 v28, s5, v86
	v_add_u32_e32 v53, v28, v105
	ds_read_b128 v[28:31], v53
	ds_read_b128 v[32:35], v53 offset:64
	ds_read_b128 v[36:39], v53 offset:3328
	ds_read_b128 v[120:123], v53 offset:128
	ds_read_b128 v[40:43], v53 offset:6656
	ds_read_b128 v[44:47], v53 offset:6720
	ds_read_b128 v[48:51], v53 offset:9984
	ds_read_b128 v[80:83], v53 offset:6784
	s_waitcnt lgkmcnt(1)
	v_mfma_f32_16x16x32_bf16 v[54:57], v[48:51], v[0:3], 0
	ds_read_b128 v[48:51], v53 offset:13312
	ds_read_b128 v[58:61], v53 offset:13376
	v_mov_b32_e32 v119, v52
	s_waitcnt lgkmcnt(1)
	v_mfma_f32_16x16x32_bf16 v[62:65], v[48:51], v[0:3], 0
	ds_read_b128 v[48:51], v53 offset:16640
	ds_read_b128 v[72:75], v53 offset:13440
	v_mfma_f32_16x16x32_bf16 v[28:31], v[28:31], v[0:3], 0
	s_waitcnt lgkmcnt(1)
	v_mfma_f32_16x16x32_bf16 v[68:71], v[48:51], v[0:3], 0
	ds_read_b128 v[48:51], v53 offset:19968
	ds_read_b128 v[124:127], v53 offset:20032
	v_mfma_f32_16x16x32_bf16 v[36:39], v[36:39], v[0:3], 0
	s_waitcnt lgkmcnt(1)
	v_mfma_f32_16x16x32_bf16 v[128:131], v[48:51], v[0:3], 0
	ds_read_b128 v[76:79], v53 offset:23296
	ds_read_b128 v[48:51], v53 offset:20096
	v_mfma_f32_16x16x32_bf16 v[136:139], v[32:35], v[4:7], v[28:31]
	s_nop 2
	ds_read_b128 v[28:31], v53 offset:3392
	ds_read_b128 v[140:143], v53 offset:3456
	v_lshl_add_u64 v[32:33], v[66:67], 1, v[92:93]
	v_lshl_add_u64 v[34:35], v[148:149], 1, v[94:95]
	s_waitcnt lgkmcnt(1)
	v_mfma_f32_16x16x32_bf16 v[144:147], v[28:31], v[4:7], v[36:39]
	ds_read_b128 v[28:31], v53 offset:10048
	ds_read_b128 v[152:155], v53 offset:10112
	v_mfma_f32_16x16x32_bf16 v[40:43], v[40:43], v[0:3], 0
	v_mfma_f32_16x16x32_bf16 v[132:135], v[76:79], v[0:3], 0
	s_waitcnt lgkmcnt(1)
	v_mfma_f32_16x16x32_bf16 v[156:159], v[28:31], v[4:7], v[54:57]
	v_mfma_f32_16x16x32_bf16 v[76:79], v[58:61], v[4:7], v[62:65]
	ds_read_b128 v[28:31], v53 offset:16704
	s_nop 1
	ds_read_b128 v[64:67], v53 offset:16768
	v_mfma_f32_16x16x32_bf16 v[148:151], v[44:47], v[4:7], v[40:43]
	v_lshl_add_u64 v[44:45], v[106:107], 0, s[20:21]
	v_lshl_add_u64 v[46:47], v[112:113], 0, s[20:21]
	s_nop 0
	v_lshl_add_u64 v[40:41], v[160:161], 1, v[96:97]
	s_waitcnt lgkmcnt(1)
	v_mfma_f32_16x16x32_bf16 v[68:71], v[28:31], v[4:7], v[68:71]
	global_load_dwordx4 v[36:39], v[32:33], off
	s_nop 0
	global_load_dwordx4 v[32:35], v[34:35], off
	s_nop 0
	global_load_dwordx4 v[28:31], v[40:41], off
	ds_read_b128 v[40:43], v53 offset:23360
	ds_read_b128 v[52:55], v53 offset:23424
	s_waitcnt lgkmcnt(1)
	v_mfma_f32_16x16x32_bf16 v[56:59], v[40:43], v[4:7], v[132:135]
	global_load_dwordx4 v[40:43], v[44:45], off
	s_nop 0
	global_load_dwordx4 v[44:47], v[46:47], off
	v_mfma_f32_16x16x32_bf16 v[120:123], v[120:123], v[8:11], v[136:139]
	v_mfma_f32_16x16x32_bf16 v[60:63], v[124:127], v[4:7], v[128:131]
	v_or_b32_e32 v124, s5, v102
	s_nop 1
	v_add_u32_e32 v128, v124, v111
	v_mfma_f32_16x16x32_bf16 v[124:127], v[140:143], v[8:11], v[144:147]
	v_add_u32_e32 v172, 0x6800, v128
	v_add_u32_e32 v176, 0x7800, v128
	v_add_u32_e32 v177, 0x8800, v128
	s_waitcnt lgkmcnt(0)
	v_mfma_f32_16x16x32_bf16 v[52:55], v[52:55], v[8:11], v[56:59]
	v_add_u32_e32 v180, 0x9800, v128
	ds_read_b64 v[128:129], v172
	ds_read_b64 v[130:131], v172 offset:32
	ds_read_b64 v[132:133], v176 offset:256
	ds_read_b64 v[134:135], v176 offset:288
	ds_read_b64 v[136:137], v177 offset:512
	ds_read_b64 v[138:139], v177 offset:544
	ds_read_b64 v[140:141], v180 offset:768
	ds_read_b64 v[142:143], v180 offset:800
	v_max_f32_e32 v56, v121, v121
	v_max_f32_e32 v57, v120, v120
	v_mfma_f32_16x16x32_bf16 v[80:83], v[80:83], v[8:11], v[148:151]
	v_max_f32_e32 v56, v57, v56
	v_max3_f32 v56, v56, v122, v123
	v_max3_f32 v56, v56, v124, v125
	v_mfma_f32_16x16x32_bf16 v[144:147], v[152:155], v[8:11], v[156:159]
	v_max3_f32 v56, v56, v126, v127
	s_nop 2
	v_max3_f32 v56, v56, v80, v81
	v_max3_f32 v56, v56, v82, v83
	v_mfma_f32_16x16x32_bf16 v[72:75], v[72:75], v[8:11], v[76:79]
	ds_read_b64 v[148:149], v172 offset:64
	ds_read_b64 v[150:151], v172 offset:96
	ds_read_b64 v[152:153], v176 offset:320
	ds_read_b64 v[154:155], v176 offset:352
	ds_read_b64 v[156:157], v177 offset:576
	ds_read_b64 v[158:159], v177 offset:608
	v_max3_f32 v56, v56, v144, v145
	v_max3_f32 v56, v56, v146, v147
	v_mfma_f32_16x16x32_bf16 v[64:67], v[64:67], v[8:11], v[68:71]
	s_nop 1
	v_max3_f32 v56, v56, v72, v73
	v_max3_f32 v56, v56, v74, v75
	ds_read_b64 v[76:77], v180 offset:832
	ds_read_b64 v[78:79], v180 offset:864
	ds_read_b64 v[160:161], v172 offset:128
	ds_read_b64 v[162:163], v172 offset:160
	ds_read_b64 v[164:165], v176 offset:384
	ds_read_b64 v[166:167], v176 offset:416
	v_mfma_f32_16x16x32_bf16 v[48:51], v[48:51], v[8:11], v[60:63]
	v_max3_f32 v56, v56, v64, v65
	v_max3_f32 v56, v56, v66, v67
	ds_read_b64 v[68:69], v177 offset:640
	ds_read_b64 v[70:71], v177 offset:672
	ds_read_b64 v[168:169], v180 offset:896
	ds_read_b64 v[170:171], v180 offset:928
	ds_read_b64 v[174:175], v172 offset:224
	ds_read_b64 v[172:173], v172 offset:192
	s_nop 2
	v_max3_f32 v56, v56, v48, v49
	v_max3_f32 v56, v56, v50, v51
	v_max3_f32 v56, v56, v52, v53
	v_max3_f32 v56, v56, v54, v55
	v_mov_b32_e32 v57, v56
	s_nop 1
	v_permlane16_swap_b32_e32 v56, v57
	v_max_f32_e32 v57, v57, v57
	v_max_f32_e32 v56, v56, v56
	v_max_f32_e32 v56, v56, v57
	v_mov_b32_e32 v57, v56
	s_nop 1
	v_permlane32_swap_b32_e32 v56, v57
	v_max3_f32 v184, v118, v56, v57
	v_sub_f32_e32 v118, v118, v184
	v_sub_f32_e32 v56, v120, v184
	v_sub_f32_e32 v57, v124, v184
	v_sub_f32_e32 v58, v121, v184
	v_sub_f32_e32 v59, v125, v184
	v_sub_f32_e32 v120, v122, v184
	v_sub_f32_e32 v121, v126, v184
	v_sub_f32_e32 v122, v123, v184
	v_sub_f32_e32 v123, v127, v184
	v_sub_f32_e32 v125, v145, v184
	v_sub_f32_e32 v127, v147, v184
	v_sub_f32_e32 v145, v64, v184
	v_sub_f32_e32 v147, v65, v184
	v_sub_f32_e32 v186, v66, v184
	v_sub_f32_e32 v188, v67, v184
	v_exp_f32_e32 v56, v56
	v_exp_f32_e32 v57, v57
	v_exp_f32_e32 v58, v58
	v_exp_f32_e32 v59, v59
	v_exp_f32_e32 v64, v120
	v_exp_f32_e32 v65, v121
	v_exp_f32_e32 v66, v122
	v_exp_f32_e32 v67, v123
	v_exp_f32_e32 v118, v118
	v_sub_f32_e32 v80, v80, v184
	v_sub_f32_e32 v124, v144, v184
	v_sub_f32_e32 v81, v81, v184
	v_sub_f32_e32 v82, v82, v184
	v_sub_f32_e32 v126, v146, v184
	v_sub_f32_e32 v83, v83, v184
	v_sub_f32_e32 v144, v72, v184
	v_sub_f32_e32 v146, v73, v184
	v_sub_f32_e32 v185, v74, v184
	v_sub_f32_e32 v187, v75, v184
	v_sub_f32_e32 v189, v48, v184
	v_sub_f32_e32 v191, v49, v184
	v_sub_f32_e32 v193, v50, v184
	v_sub_f32_e32 v195, v51, v184
	v_exp_f32_e32 v72, v80
	v_exp_f32_e32 v73, v124
	v_exp_f32_e32 v74, v81
	v_exp_f32_e32 v75, v125
	v_exp_f32_e32 v80, v82
	v_exp_f32_e32 v81, v126
	v_exp_f32_e32 v82, v83
	v_exp_f32_e32 v83, v127
	v_mul_f32_e32 v26, v26, v118
	v_mul_f32_e32 v27, v27, v118
	v_mul_f32_e32 v24, v24, v118
	v_mul_f32_e32 v25, v25, v118
	v_cvt_pk_bf16_f32 v48, v56, v58
	v_cvt_pk_bf16_f32 v49, v64, v66
	v_cvt_pk_bf16_f32 v50, v57, v59
	v_cvt_pk_bf16_f32 v51, v65, v67
	v_mul_f32_e32 v22, v22, v118
	v_mul_f32_e32 v23, v23, v118
	v_mul_f32_e32 v20, v20, v118
	v_mul_f32_e32 v21, v21, v118
	v_mul_f32_e32 v18, v18, v118
	v_mul_f32_e32 v19, v19, v118
	v_mul_f32_e32 v16, v16, v118
	v_mul_f32_e32 v17, v17, v118
	v_mul_f32_e32 v14, v14, v118
	v_mul_f32_e32 v15, v15, v118
	v_mul_f32_e32 v12, v12, v118
	v_mul_f32_e32 v13, v13, v118
	s_waitcnt lgkmcnt(15)
	v_mfma_f32_16x16x32_bf16 v[24:27], v[128:131], v[48:51], v[24:27]
	v_sub_f32_e32 v190, v52, v184
	v_sub_f32_e32 v192, v53, v184
	v_sub_f32_e32 v194, v54, v184
	s_waitcnt lgkmcnt(15)
	v_mfma_f32_16x16x32_bf16 v[20:23], v[132:135], v[48:51], v[20:23]
	v_sub_f32_e32 v196, v55, v184
	v_exp_f32_e32 v120, v144
	v_exp_f32_e32 v121, v145
	s_waitcnt lgkmcnt(15)
	v_mfma_f32_16x16x32_bf16 v[16:19], v[136:139], v[48:51], v[16:19]
	v_exp_f32_e32 v122, v146
	v_exp_f32_e32 v123, v147
	v_exp_f32_e32 v124, v185
	s_waitcnt lgkmcnt(15)
	v_mfma_f32_16x16x32_bf16 v[12:15], v[140:143], v[48:51], v[12:15]
	v_cvt_pk_bf16_f32 v52, v72, v74
	v_cvt_pk_bf16_f32 v53, v80, v82
	v_cvt_pk_bf16_f32 v54, v73, v75
	v_cvt_pk_bf16_f32 v55, v81, v83
	v_exp_f32_e32 v125, v186
	v_exp_f32_e32 v126, v187
	v_exp_f32_e32 v127, v188
	s_waitcnt lgkmcnt(15)
	v_mfma_f32_16x16x32_bf16 v[24:27], v[148:151], v[52:55], v[24:27]
	v_cvt_pk_bf16_f32 v48, v120, v122
	v_cvt_pk_bf16_f32 v49, v124, v126
	s_waitcnt lgkmcnt(14)
	v_mfma_f32_16x16x32_bf16 v[20:23], v[152:155], v[52:55], v[20:23]
	v_cvt_pk_bf16_f32 v50, v121, v123
	v_cvt_pk_bf16_f32 v51, v125, v127
	v_add_f32_e32 v56, v58, v56
	v_add_f32_e32 v57, v59, v57
	s_waitcnt lgkmcnt(12)
	v_mfma_f32_16x16x32_bf16 v[16:19], v[156:159], v[52:55], v[16:19]
	v_exp_f32_e32 v128, v189
	v_exp_f32_e32 v129, v190
	ds_read_b64 v[60:61], v176 offset:448
	ds_read_b64 v[62:63], v176 offset:480
	ds_read_b64 v[178:179], v177 offset:736
	ds_read_b64 v[176:177], v177 offset:704
	ds_read_b64 v[182:183], v180 offset:992
	ds_read_b64 v[180:181], v180 offset:960
	s_waitcnt lgkmcnt(15)
	v_mfma_f32_16x16x32_bf16 v[12:15], v[76:79], v[52:55], v[12:15]
	v_exp_f32_e32 v130, v191
	v_exp_f32_e32 v131, v192
	v_exp_f32_e32 v132, v193
	s_waitcnt lgkmcnt(14)
	v_mfma_f32_16x16x32_bf16 v[24:27], v[160:163], v[48:51], v[24:27]
	v_exp_f32_e32 v133, v194
	v_exp_f32_e32 v76, v195
	v_exp_f32_e32 v77, v196
	s_waitcnt lgkmcnt(12)
	v_mfma_f32_16x16x32_bf16 v[20:23], v[164:167], v[48:51], v[20:23]
	v_cvt_pk_bf16_f32 v52, v128, v130
	v_cvt_pk_bf16_f32 v53, v132, v76
	v_cvt_pk_bf16_f32 v54, v129, v131
	s_waitcnt lgkmcnt(10)
	v_mfma_f32_16x16x32_bf16 v[16:19], v[68:71], v[48:51], v[16:19]
	v_cvt_pk_bf16_f32 v55, v133, v77
	s_waitcnt lgkmcnt(8)
	v_mfma_f32_16x16x32_bf16 v[12:15], v[168:171], v[48:51], v[12:15]
	v_add_f32_e64 v48, v64, v56
	v_add_f32_e64 v49, v65, v57
	v_add_f32_e32 v48, v66, v48
	v_add_f32_e32 v49, v67, v49
	s_waitcnt lgkmcnt(6)
	v_mfma_f32_16x16x32_bf16 v[24:27], v[172:175], v[52:55], v[24:27]
	v_add_f32_e64 v48, v72, v48
	v_add_f32_e64 v49, v73, v49
	v_add_f32_e32 v48, v74, v48
	v_add_f32_e32 v49, v75, v49
	s_waitcnt lgkmcnt(4)
	v_mfma_f32_16x16x32_bf16 v[20:23], v[60:63], v[52:55], v[20:23]
	v_add_f32_e64 v48, v80, v48
	v_add_f32_e64 v49, v81, v49
	v_add_f32_e32 v48, v82, v48
	v_add_f32_e32 v49, v83, v49
	s_waitcnt lgkmcnt(2)
	v_mfma_f32_16x16x32_bf16 v[16:19], v[176:179], v[52:55], v[16:19]
	v_add_f32_e64 v48, v120, v48
	v_add_f32_e64 v49, v121, v49
	v_add_f32_e32 v48, v122, v48
	v_add_f32_e32 v49, v123, v49
	s_waitcnt lgkmcnt(0)
	v_mfma_f32_16x16x32_bf16 v[12:15], v[180:183], v[52:55], v[12:15]
	v_add_f32_e64 v48, v124, v48
	v_add_f32_e64 v49, v125, v49
	v_add_f32_e32 v48, v126, v48
	v_add_f32_e32 v49, v127, v49
	v_add_f32_e32 v48, v128, v48
	v_add_f32_e32 v49, v129, v49
	v_add_f32_e32 v48, v130, v48
	v_add_f32_e32 v49, v131, v49
	v_add_f32_e32 v48, v132, v48
	v_add_f32_e32 v49, v133, v49
	v_add_f32_e32 v48, v76, v48
	v_add_f32_e32 v49, v77, v49
	v_add_f32_e32 v52, v48, v49
	v_fmac_f32_e32 v52, v119, v118
	s_bitcmp1_b32 s4, 0
	s_cselect_b32 s5, 0xac00, 0
	v_add3_u32 v48, s5, v114, v101
	s_waitcnt vmcnt(4)
	ds_write_b128 v48, v[36:39]
	v_add3_u32 v36, s5, v115, v103
	s_waitcnt vmcnt(3)
	ds_write_b128 v36, v[32:35]
	v_add3_u32 v32, s5, v116, v99
	s_waitcnt vmcnt(2)
	ds_write_b128 v32, v[28:31]
	v_add3_u32 v28, s5, v117, v104
	s_cmp_lg_u32 s33, s4
	v_mov_b32_e32 v118, v184
	s_mov_b32 s7, s4
	s_waitcnt vmcnt(1)
	ds_write_b128 v28, v[40:43] offset:26624
	s_waitcnt vmcnt(0)
	ds_write_b128 v28, v[44:47] offset:35328
	s_waitcnt lgkmcnt(0)
	s_barrier
	s_cbranch_scc1 .LBB0_929
	v_mov_b32_e32 v0, v52
	s_nop 1
	v_permlane16_swap_b32_e32 v52, v0
	v_add_f32_e32 v0, v52, v0
	v_mov_b32_e32 v1, v0
	s_nop 1
	v_permlane32_swap_b32_e32 v0, v1
	v_add_f32_e32 v0, v0, v1
	v_div_scale_f32 v1, s[4:5], v0, v0, 1.0
	v_rcp_f32_e32 v2, v1
	v_mov_b32_e32 v99, v87
	v_lshlrev_b64 v[8:9], 1, v[98:99]
	v_mov_b32_e32 v103, v87
	v_fma_f32 v3, -v1, v2, 1.0
	v_fmac_f32_e32 v2, v3, v2
	v_div_scale_f32 v3, vcc, 1.0, v0, 1.0
	v_mul_f32_e32 v4, v3, v2
	v_fma_f32 v5, -v1, v4, v3
	v_fmac_f32_e32 v4, v5, v2
	v_fma_f32 v1, -v1, v4, v3
	v_div_fmas_f32 v1, v1, v2, v4
	v_div_fixup_f32 v0, v1, v0, 1.0
	v_lshlrev_b64 v[2:3], 11, v[90:91]
	v_pk_mul_f32 v[4:5], v[24:25], v[0:1] op_sel_hi:[1,0]
	v_pk_mul_f32 v[6:7], v[26:27], v[0:1] op_sel_hi:[1,0]
	v_cvt_pk_bf16_f32 v4, v4, v5
	v_cvt_pk_bf16_f32 v5, v6, v7
	v_lshl_add_u64 v[6:7], s[16:17], 0, v[2:3]
	v_lshl_add_u64 v[2:3], s[34:35], 0, v[2:3]
	v_lshl_add_u64 v[6:7], v[6:7], 0, v[8:9]
	v_lshl_add_u64 v[2:3], v[2:3], 0, v[8:9]
	v_lshl_add_u64 v[6:7], v[6:7], 0, v[102:103]
	v_lshl_add_u64 v[2:3], v[2:3], 0, v[102:103]
	global_store_dwordx2 v[6:7], v[4:5], off
	v_pk_mul_f32 v[4:5], v[20:21], v[0:1] op_sel_hi:[1,0]
	v_pk_mul_f32 v[6:7], v[22:23], v[0:1] op_sel_hi:[1,0]
	v_add_co_u32_e32 v2, vcc, s30, v2
	v_cvt_pk_bf16_f32 v4, v4, v5
	v_cvt_pk_bf16_f32 v5, v6, v7
	v_addc_co_u32_e32 v3, vcc, 0, v3, vcc
	global_store_dwordx2 v[2:3], v[4:5], off offset:32
	v_pk_mul_f32 v[4:5], v[16:17], v[0:1] op_sel_hi:[1,0]
	v_pk_mul_f32 v[6:7], v[18:19], v[0:1] op_sel_hi:[1,0]
	v_cvt_pk_bf16_f32 v4, v4, v5
	v_cvt_pk_bf16_f32 v5, v6, v7
	global_store_dwordx2 v[2:3], v[4:5], off offset:64
	v_pk_mul_f32 v[4:5], v[12:13], v[0:1] op_sel_hi:[1,0]
	v_pk_mul_f32 v[0:1], v[14:15], v[0:1] op_sel_hi:[1,0]
	v_cvt_pk_bf16_f32 v4, v4, v5
	v_cvt_pk_bf16_f32 v5, v0, v1
	global_store_dwordx2 v[2:3], v[4:5], off offset:96
	s_load_dword s6, s[18:19], 0x0
	s_waitcnt lgkmcnt(0)
	s_add_i32 s31, s6, s31
	s_cmpk_gt_i32 s31, 0x1ff
	s_cbranch_scc0 .LBB0_912
